# NSA tile: V^T tile stored with 144-B rows and per-chunk key order matching the packed-P operand, fragments read with one ds_read_b128 instead of ds_read2_b64
# speedup vs baseline: 1.0102x; 1.0102x over previous
; #define LAS __attribute__((address_space(3)))
; DI void nsa_attn_phase(int wv, LAS unsigned char* lds, const bf16_t* Q, const bf16_t* slab, const bf16_t* VT2, const float* gates, const bf16_t* KCMP, const bf16_t* VCMPT,
;                        const float* rel_bias, bf16_t* O) {
;     ...
;                 auto gload = [&](int j) {
;                     rk = *(const u32x4*)(Ksrc + (size_t)j * 64 * 64 + (size_t)tid * 8);
;                     rv = *(const u32x4*)(Vsrc + (size_t)(tid >> 3) * VPITCH + 64 * j + (tid & 7) * 8);
;                 };
;                 auto lstore = [&](int buf) {
;                     LAS unsigned char* kb = lds + OFF_BUF + buf * TILE;
;                     *(LAS u32x4*)(kb + (tid >> 3) * KS + (tid & 7) * 16) = rk;
;                     lds_store16_as2x8(kb + VOFF + (tid >> 3) * VS + (tid & 7) * 16, rv);
;                 };
.LBB0_2414:
	s_max_i32 s1, s26, 8
	s_add_i32 s1, s1, -8
	s_lshl_b32 s1, -1, s1
	v_ashrrev_i32_e32 v0, 3, v114
	v_mov_b64_e32 v[2:3], s[14:15]
	s_and_b32 s91, s0, s1
	v_mad_i64_i32 v[216:217], s[0:1], v0, s43, v[2:3]
	v_lshlrev_b32_e32 v2, 3, v114
	v_mul_lo_u32 v236, v0, s87
	v_and_b32_e32 v204, 56, v2
	v_add_u32_e32 v237, 0, v236
	v_lshlrev_b32_e32 v2, 4, v114
	v_mul_lo_u32 v239, v0, s94
	v_and_b32_e32 v0, -8, v114
	v_ashrrev_i32_e32 v115, 31, v114
	v_and_b32_e32 v238, 0x70, v2
	v_sub_u32_e32 v0, v237, v0
	v_cmp_gt_u32_e64 s[2:3], 32, v118
	v_lshlrev_b64 v[214:215], 4, v[114:115]
	s_sub_i32 s92, s90, 63
	s_or_b32 s93, s90, 31
	v_cvt_pk_bf16_f32 v240, v113, s0
	v_cndmask_b32_e64 v192, 0, v232, s[2:3]
	v_cndmask_b32_e64 v193, 0, v228, s[2:3]
	v_mov_b32_e32 v194, v1
	v_mov_b32_e32 v195, v1
	v_mul_u32_u24_e32 v241, 0x90, v112
	v_mul_u32_u24_e32 v242, 0x88, v112
	s_mov_b64 s[8:9], -1
	v_lshlrev_b32_e32 v2, 4, v114
	v_and_b32_e32 v2, 0x60, v2
	v_and_b32_e32 v3, 1, v114
	v_lshl_or_b32 v2, v3, 3, v2
	v_add_u32_e32 v239, v236, v2
	v_add_u32_e32 v243, s62, v239
	s_branch .LBB0_2416

; #define LAS __attribute__((address_space(3)))
; DI void nsa_attn_phase(int wv, LAS unsigned char* lds, const bf16_t* Q, const bf16_t* slab, const bf16_t* VT2, const float* gates, const bf16_t* KCMP, const bf16_t* VCMPT,
;                        const float* rel_bias, bf16_t* O) {
;     ...
;                 const bf16_t* Ksrc = slab + (size_t)(br ? 3 : 2) * SLAB_EL + bg * 2048 * 64;
;                 const bf16_t* Vsrc = VT2 + ((size_t)b * 512 + (br ? 256 : 0) + g * 64) * VPITCH;
;                 unsigned tiles;
;                 if (br == 0) tiles = uni; else { const int jlo = qblk - 8 < 0 ? 0 : qblk - 8; tiles = causal & ~((1u << jlo) - 1u); }
;                 float m = 0.f, l = 0.f; f32x16 o[2] = {zero16(), zero16()};
;                 u32x4 rk, rv;
;                 auto gload = [&](int j) {
;                     rk = *(const u32x4*)(Ksrc + (size_t)j * 64 * 64 + (size_t)tid * 8);
;                     rv = *(const u32x4*)(Vsrc + (size_t)(tid >> 3) * VPITCH + 64 * j + (tid & 7) * 8);
;                 };
;                 auto lstore = [&](int buf) {
;                     LAS unsigned char* kb = lds + OFF_BUF + buf * TILE;
;                     *(LAS u32x4*)(kb + (tid >> 3) * KS + (tid & 7) * 16) = rk;
;                     lds_store16_as2x8(kb + VOFF + (tid >> 3) * VS + (tid & 7) * 16, rv);
;                 };
;                 auto process = [&](const LAS unsigned char* kb, int j) {
;                     const int k0 = 64 * j;
;                     const bool selbit = (br == 0) ? (((mysel >> j) & 1u) != 0u) : true;
;                     if (br == 0 && __ballot(selbit) == 0ull) return;
;                     const bool far = (TW - (k0 + 63) >= 127) && (br == 0 || (TW + 31 - k0 < 512));
;                     f32x16 s[2];
;                     qk_tile<4>(kb, KS, qf, s, r, hh, ref_frag(-m, far ? (selbit ? c31 : NEGF) : 0.f, hh));
;                     if (!far) {
;                         const int d0 = tq - k0 - 4 * hh;
; #pragma unroll
;                         for (int t = 0; t < 2; ++t)
; #pragma unroll
;                             for (int i = 0; i < 16; ++i) {
;                                 const int dist = d0 - (32 * t + (i & 3) + 8 * (i >> 2));
;                                 const float bias = mylut[dist < 0 ? 0 : (dist > 127 ? 127 : dist)];
;                                 const bool valid = selbit && dist >= 0 && (br == 0 || dist < 512);
.LBB0_2416:
	s_and_b64 s[0:1], s[8:9], exec
	s_brev_b32 s0, 64
	s_cselect_b32 s0, s0, 0x3000000
	v_mov_b32_e32 v0, s91
	s_add_u32 s4, s69, s0
	v_cndmask_b32_e64 v0, v0, v234, s[8:9]
	s_addc_u32 s5, s84, 0
	v_ffbl_b32_e32 v144, v0
	v_add_u32_e32 v2, -1, v0
	s_and_b64 s[0:1], s[8:9], exec
	v_and_b32_e32 v4, v2, v0
	v_lshlrev_b32_e32 v0, 13, v144
	s_cselect_b32 s0, 0, 0x100
	v_lshl_add_u64 v[2:3], s[4:5], 0, v[0:1]
	s_or_b32 s0, s0, s22
	v_lshl_add_u64 v[2:3], v[2:3], 0, v[214:215]
	v_mov_b32_e32 v0, 0x1080
	s_waitcnt vmcnt(0)
	flat_load_dwordx4 v[196:199], v[2:3]
	v_mad_u64_u32 v[2:3], s[0:1], s0, v0, v[216:217]
	s_mul_i32 s0, s23, 0x1080
	s_nop 0
	v_add_u32_e32 v3, s0, v3
	v_lshlrev_b32_e32 v0, 7, v144
	v_lshl_add_u64 v[6:7], v[2:3], 0, v[0:1]
	v_lshlrev_b32_e32 v0, 1, v204
	v_lshl_add_u64 v[6:7], v[6:7], 0, v[0:1]
	flat_load_dwordx4 v[200:203], v[6:7]
	v_mov_b32_e32 v244, -1
	v_add_u32_e32 v5, v237, v238
	v_cmp_ne_u32_e32 vcc, 0, v4
	v_mov_b32_e32 v245, 0
	v_mov_b32_e32 v145, 0
	s_waitcnt vmcnt(0) lgkmcnt(0)
	ds_write_b128 v5, v[196:199] offset:35328
	ds_write2_b64 v243, v[200:201], v[202:203] offset1:2
	s_and_saveexec_b64 s[6:7], vcc
	s_cbranch_execz .LBB0_2418
	v_ffbl_b32_e32 v244, v4
	v_lshlrev_b32_e32 v6, 13, v244
	v_mov_b32_e32 v7, v1
	v_lshl_add_u64 v[6:7], s[4:5], 0, v[6:7]
	v_lshlrev_b32_e32 v8, 7, v244
	v_mov_b32_e32 v9, v1
	v_lshl_add_u64 v[6:7], v[6:7], 0, v[214:215]
	v_lshl_add_u64 v[8:9], v[2:3], 0, v[8:9]
	v_lshl_add_u64 v[8:9], v[8:9], 0, v[0:1]
	flat_load_dwordx4 v[196:199], v[6:7]
	flat_load_dwordx4 v[200:203], v[8:9]
	v_add_u32_e32 v5, -1, v4
	v_and_b32_e32 v145, v5, v4

; #define LAS __attribute__((address_space(3)))
; DI float fexp2(float x) { return __builtin_amdgcn_exp2f(x); }
; DI f32x16 mfma32(bf16x8 a, bf16x8 b, f32x16 c) { return __builtin_amdgcn_mfma_f32_32x32x16_bf16(a, b, c, 0, 0, 0); }
; DI void pv_sub(const LAS unsigned char* vt, int vstride, int koff_bytes, const f32x16& p, f32x16 (&o)[2], int r, int hh) {
;     const bf16x8 pf0 = pack8<0>(p), pf1 = pack8<1>(p);
; #pragma unroll
;     for (int st = 0; st < 2; ++st) {
;         u32x2 lo[2], hi[2];
; #pragma unroll
;         for (int u = 0; u < 2; ++u) {
;             const LAS unsigned char* a = vt + (32 * u + r) * vstride + koff_bytes + 32 * st + 8 * hh;
;             lo[u] = *(const LAS u32x2*)a; hi[u] = *(const LAS u32x2*)(a + 16);
;         }
;         __builtin_amdgcn_sched_barrier(0);
; #pragma unroll
;         for (int u = 0; u < 2; ++u) { u32x4 v; v.x = lo[u].x; v.y = lo[u].y; v.z = hi[u].x; v.w = hi[u].y; o[u] = mfma32(__builtin_bit_cast(bf16x8, v), st ? pf1 : pf0, o[u]); }
;     }
; DI void softmax_lazy(f32x16 (&s)[2], float& m, float& l, f32x16 (&o)[2], int hh) {
;     ...
;     float sum = 0.f;
; #pragma unroll
;     for (int t = 0; t < 2; ++t)
; #pragma unroll
;         for (int i = 0; i < 16; ++i) { s[t][i] = fexp2(s[t][i]); sum += s[t][i]; }
;     sum += __shfl_xor(sum, 32);
;     l += sum;
.LBB0_2419:
	v_add3_u32 v0, s0, v212, v241
	ds_read_b128 v[56:59], v0 offset:44544
	ds_read_b128 v[60:63], v0 offset:49152
	v_exp_f32_e32 v160, v160
	v_exp_f32_e32 v161, v161
	v_exp_f32_e32 v162, v162
	v_exp_f32_e32 v163, v163
	v_exp_f32_e32 v164, v164
	v_exp_f32_e32 v165, v165
	v_exp_f32_e32 v166, v166
	v_exp_f32_e32 v167, v167
	v_add_f32_e32 v3, v161, v160
	v_add_f32_e32 v3, v162, v3
	v_add_f32_e32 v3, v163, v3
	v_add_f32_e32 v3, v164, v3
	v_add_f32_e32 v3, v165, v3
	v_add_f32_e32 v3, v166, v3
	v_add_f32_e32 v3, v167, v3
	v_cvt_pk_bf16_f32 v8, v160, v161
	v_cvt_pk_bf16_f32 v9, v162, v163
	v_cvt_pk_bf16_f32 v10, v164, v165
	v_cvt_pk_bf16_f32 v11, v166, v167
	v_exp_f32_e32 v168, v168
	v_exp_f32_e32 v169, v169
	v_exp_f32_e32 v170, v170
	v_exp_f32_e32 v171, v171
	s_waitcnt lgkmcnt(0)
	v_mfma_f32_32x32x16_bf16 v[128:143], v[56:59], v[8:11], v[128:143]
	v_exp_f32_e32 v172, v172
	v_exp_f32_e32 v173, v173
	v_exp_f32_e32 v174, v174
	v_exp_f32_e32 v175, v175
	v_mfma_f32_32x32x16_bf16 v[112:127], v[60:63], v[8:11], v[112:127]
	ds_read_b128 v[64:67], v0 offset:44576
	ds_read_b128 v[68:71], v0 offset:49184
	v_add_f32_e32 v3, v168, v3
	v_add_f32_e32 v3, v169, v3
	v_add_f32_e32 v3, v170, v3
	v_add_f32_e32 v3, v171, v3
	v_add_f32_e32 v3, v172, v3
	v_add_f32_e32 v3, v173, v3
	v_add_f32_e32 v3, v174, v3
	v_add_f32_e32 v3, v175, v3
	v_cvt_pk_bf16_f32 v12, v168, v169
	v_cvt_pk_bf16_f32 v13, v170, v171
	v_cvt_pk_bf16_f32 v14, v172, v173
	v_cvt_pk_bf16_f32 v15, v174, v175
	v_exp_f32_e32 v144, v144
	v_exp_f32_e32 v145, v145
	v_exp_f32_e32 v146, v146
	v_exp_f32_e32 v147, v147
	s_waitcnt lgkmcnt(0)
	v_mfma_f32_32x32x16_bf16 v[128:143], v[64:67], v[12:15], v[128:143]
	v_exp_f32_e32 v148, v148
	v_exp_f32_e32 v149, v149
	v_exp_f32_e32 v150, v150
	v_exp_f32_e32 v151, v151
	v_mfma_f32_32x32x16_bf16 v[112:127], v[68:71], v[12:15], v[112:127]
	ds_read_b128 v[72:75], v0 offset:44608
	ds_read_b128 v[76:79], v0 offset:49216
	v_add_f32_e32 v3, v144, v3
	v_add_f32_e32 v3, v145, v3
	v_add_f32_e32 v3, v146, v3
	v_add_f32_e32 v3, v147, v3
	v_add_f32_e32 v3, v148, v3
	v_add_f32_e32 v3, v149, v3
	v_add_f32_e32 v3, v150, v3
	v_add_f32_e32 v3, v151, v3
	v_cvt_pk_bf16_f32 v16, v144, v145
	v_cvt_pk_bf16_f32 v17, v146, v147
	v_cvt_pk_bf16_f32 v18, v148, v149
	v_cvt_pk_bf16_f32 v19, v150, v151
	v_exp_f32_e32 v152, v152
	v_exp_f32_e32 v153, v153
	v_exp_f32_e32 v154, v154
	v_exp_f32_e32 v155, v155
	s_waitcnt lgkmcnt(0)
	v_mfma_f32_32x32x16_bf16 v[128:143], v[72:75], v[16:19], v[128:143]
	v_exp_f32_e32 v156, v156
	v_exp_f32_e32 v157, v157
	v_exp_f32_e32 v158, v158
	v_exp_f32_e32 v159, v159
	v_mfma_f32_32x32x16_bf16 v[112:127], v[76:79], v[16:19], v[112:127]
	ds_read_b128 v[144:147], v0 offset:44640
	ds_read_b128 v[148:151], v0 offset:49248
	v_add_f32_e32 v3, v152, v3
	v_add_f32_e32 v3, v153, v3
	v_add_f32_e32 v3, v154, v3
	v_add_f32_e32 v3, v155, v3
	v_add_f32_e32 v3, v156, v3
	v_add_f32_e32 v3, v157, v3
	v_add_f32_e32 v3, v158, v3
	v_add_f32_e32 v3, v159, v3
	v_mov_b32_e32 v7, v3
	v_cvt_pk_bf16_f32 v52, v152, v153
	v_cvt_pk_bf16_f32 v53, v154, v155
	v_cvt_pk_bf16_f32 v54, v156, v157
	v_cvt_pk_bf16_f32 v55, v158, v159
	v_permlane32_swap_b32_e32 v7, v3
	v_add_f32_e32 v3, v3, v7
	v_add_f32_e32 v245, v245, v3
	s_waitcnt lgkmcnt(0)
	v_mfma_f32_32x32x16_bf16 v[128:143], v[144:147], v[52:55], v[128:143]
	v_mfma_f32_32x32x16_bf16 v[112:127], v[148:151], v[52:55], v[112:127]

; #define LAS __attribute__((address_space(3)))
; DI void nsa_attn_phase(int wv, LAS unsigned char* lds, const bf16_t* Q, const bf16_t* slab, const bf16_t* VT2, const float* gates, const bf16_t* KCMP, const bf16_t* VCMPT,
;                        const float* rel_bias, bf16_t* O) {
;     ...
;                 auto lstore = [&](int buf) {
;                     LAS unsigned char* kb = lds + OFF_BUF + buf * TILE;
;                     *(LAS u32x4*)(kb + (tid >> 3) * KS + (tid & 7) * 16) = rk;
;                     lds_store16_as2x8(kb + VOFF + (tid >> 3) * VS + (tid & 7) * 16, rv);
;                 };
;     ...
;                     const int bn = bi == 2 ? 0 : bi + 1;
;                     if (jn >= 0) lstore(bn);
.LBB0_2421:
	s_add_i32 s1, s0, 1
	s_cmp_lg_u32 s0, 2
	s_cselect_b32 s96, s1, 0
	v_cmp_lt_i32_e32 vcc, -1, v244
	s_and_saveexec_b64 s[4:5], vcc
	s_cbranch_execz .LBB0_2423
	s_mul_i32 s1, s96, 0x4800
	s_add_i32 s1, s1, 0
	v_add3_u32 v0, s1, v236, v238
	v_add_u32_e32 v2, s1, v239
	v_add_u32_e32 v2, s62, v2
	s_waitcnt vmcnt(0)
	ds_write_b128 v0, v[196:199] offset:35328
	ds_write2_b64 v2, v[200:201], v[202:203] offset1:2

; #define LAS __attribute__((address_space(3)))
; DI f32x16 mfma32(bf16x8 a, bf16x8 b, f32x16 c) { return __builtin_amdgcn_mfma_f32_32x32x16_bf16(a, b, c, 0, 0, 0); }
; DI f32x16 zero16() { f32x16 z; for (int i = 0; i < 16; ++i) z[i] = 0.f; return z; }
; template <int NKS>
; DI void qk_tile(const LAS unsigned char* kt, int kstride, const bf16x8 (&qf)[NKS], f32x16 (&s)[2], int r, int hh, const bf16x8 rf) {
;     const bf16x8 of = ones_frag(hh);
; #pragma unroll
;     for (int t = 0; t < 2; ++t) {
;         bf16x8 kf[NKS];
; #pragma unroll
;         for (int ks = 0; ks < NKS; ++ks) kf[ks] = *(const LAS bf16x8*)(kt + (32 * t + r) * kstride + 32 * ks + 16 * hh);
;         __builtin_amdgcn_sched_barrier(0);
;         s[t] = zero16();
; #pragma unroll
;         for (int ks = 0; ks < NKS; ++ks) s[t] = mfma32(kf[ks], qf[ks], s[t]);
;         s[t] = mfma32(of, rf, s[t]);
;     }
; DI void nsa_attn_phase(int wv, LAS unsigned char* lds, const bf16_t* Q, const bf16_t* slab, const bf16_t* VT2, const float* gates, const bf16_t* KCMP, const bf16_t* VCMPT,
;                        const float* rel_bias, bf16_t* O) {
;     ...
;                 auto process = [&](const LAS unsigned char* kb, int j) {
;                     const int k0 = 64 * j;
;                     const bool selbit = (br == 0) ? (((mysel >> j) & 1u) != 0u) : true;
;                     if (br == 0 && __ballot(selbit) == 0ull) return;
;                     const bool far = (TW - (k0 + 63) >= 127) && (br == 0 || (TW + 31 - k0 < 512));
;                     f32x16 s[2];
;                     qk_tile<4>(kb, KS, qf, s, r, hh, ref_frag(-m, far ? (selbit ? c31 : NEGF) : 0.f, hh));
;                     if (!far) {
;                         const int d0 = tq - k0 - 4 * hh;
; #pragma unroll
;                         for (int t = 0; t < 2; ++t)
; #pragma unroll
;                             for (int i = 0; i < 16; ++i) {
;                                 const int dist = d0 - (32 * t + (i & 3) + 8 * (i >> 2));
;                                 const float bias = mylut[dist < 0 ? 0 : (dist > 127 ? 127 : dist)];
;                                 const bool valid = selbit && dist >= 0 && (br == 0 || dist < 512);
;                                 s[t][i] = valid ? s[t][i] + bias : NEGF;
;                             }
;                     }
.LBB0_2427:
	s_andn2_b64 vcc, exec, s[6:7]
	s_cbranch_vccnz .LBB0_2420
	s_mulk_i32 s0, 0x4800
	s_add_i32 s0, s0, 0
	v_add3_u32 v7, s0, v212, v241
	ds_read_b128 v[8:11], v7 offset:35328
	ds_read_b128 v[12:15], v7 offset:35360
	ds_read_b128 v[64:67], v7 offset:35392
	ds_read_b128 v[68:71], v7 offset:35424
	ds_read_b128 v[72:75], v7 offset:39936
	ds_read_b128 v[76:79], v7 offset:39968
	ds_read_b128 v[250:253], v7 offset:40000
	ds_read_b128 v[224:227], v7 offset:40032
	v_cvt_pk_bf16_f32 v3, -v4, s0
	v_perm_b32 v3, 0, v3, v229
	v_lshlrev_b32_e32 v2, 16, v3
	v_sub_f32_e64 v2, -v4, v2
	v_cvt_pk_bf16_f32 v2, v2, s0
	v_mul_i32_i24_e32 v0, 0xffffffc0, v144
	v_lshl_or_b32 v3, v2, 16, v3
	v_add_u32_e32 v2, s92, v0
	s_movk_i32 s1, 0x7e
	v_cmp_lt_i32_e64 s[6:7], s1, v2
	v_add_u32_e32 v2, s93, v0
	v_cmp_gt_i32_e32 vcc, s83, v2
	s_or_b64 s[30:31], s[8:9], vcc
	s_or_b64 vcc, s[26:27], s[4:5]
	v_mov_b32_e32 v2, 0xfffff14a
	v_cndmask_b32_e32 v2, v2, v240, vcc
	s_and_b64 s[4:5], s[6:7], s[30:31]
	v_cndmask_b32_e64 v2, 0, v2, s[4:5]
	v_mov_b32_e32 v208, 0x1100
	v_perm_b32 v2, 0, v2, v229
	s_xor_b64 s[4:5], s[4:5], -1
	v_cndmask_b32_e64 v246, 0, v3, s[2:3]
	v_cndmask_b32_e64 v247, 0, v2, s[2:3]
	v_mov_b32_e32 v248, v1
	v_mov_b32_e32 v249, v1
	s_waitcnt lgkmcnt(7)
	v_mfma_f32_32x32x16_bf16 v[160:175], v[8:11], v[176:179], 0
	s_waitcnt lgkmcnt(6)
	v_mfma_f32_32x32x16_bf16 v[160:175], v[12:15], v[180:183], v[160:175]
	s_waitcnt lgkmcnt(5)
	v_mfma_f32_32x32x16_bf16 v[160:175], v[64:67], v[184:187], v[160:175]
	s_waitcnt lgkmcnt(4)
	v_mfma_f32_32x32x16_bf16 v[160:175], v[68:71], v[188:191], v[160:175]
	v_mfma_f32_32x32x16_bf16 v[160:175], v[192:195], v[246:249], v[160:175]
	s_waitcnt lgkmcnt(3)
	v_mfma_f32_32x32x16_bf16 v[144:159], v[72:75], v[176:179], 0
	s_waitcnt lgkmcnt(2)
	v_mfma_f32_32x32x16_bf16 v[144:159], v[76:79], v[180:183], v[144:159]
	s_waitcnt lgkmcnt(1)
	v_mfma_f32_32x32x16_bf16 v[144:159], v[250:253], v[184:187], v[144:159]
	s_waitcnt lgkmcnt(0)
	v_mfma_f32_32x32x16_bf16 v[144:159], v[224:227], v[188:191], v[144:159]
	v_mfma_f32_32x32x16_bf16 v[144:159], v[192:195], v[246:249], v[144:159]
	s_and_saveexec_b64 s[6:7], s[4:5]
	s_cbranch_execz .LBB0_2430
	v_add_u32_e32 v2, v0, v210
	v_sub_u32_e32 v2, v2, v233
	v_add_u32_e32 v2, 64, v2
	v_mov_b32_e32 v3, 63
	v_cndmask_b32_e32 v2, v3, v2, vcc
	v_lshl_add_u32 v2, v2, 2, s70
	ds_read2_b32 v[20:21], v2 offset0:59 offset1:58
	ds_read2_b32 v[22:23], v2 offset0:57 offset1:56
	ds_read2_b32 v[24:25], v2 offset0:51 offset1:50
	ds_read2_b32 v[26:27], v2 offset0:49 offset1:48
	ds_read2_b32 v[28:29], v2 offset0:43 offset1:42
	ds_read2_b32 v[30:31], v2 offset0:41 offset1:40
	ds_read2_b32 v[32:33], v2 offset0:35 offset1:34
	ds_read2_b32 v[34:35], v2 offset0:33 offset1:32
	ds_read2_b32 v[36:37], v2 offset0:27 offset1:26
	ds_read2_b32 v[38:39], v2 offset0:25 offset1:24
	ds_read2_b32 v[40:41], v2 offset0:19 offset1:18
	ds_read2_b32 v[42:43], v2 offset0:17 offset1:16
	ds_read2_b32 v[44:45], v2 offset0:11 offset1:10
	ds_read2_b32 v[46:47], v2 offset0:9 offset1:8
	ds_read2_b32 v[48:49], v2 offset0:3 offset1:2
	ds_read2_b32 v[50:51], v2 offset0:1 offset1:0
	s_waitcnt lgkmcnt(15)
	v_add_f32_e32 v160, v160, v20
	v_add_f32_e32 v161, v161, v21
	s_waitcnt lgkmcnt(14)
	v_add_f32_e32 v162, v162, v22
	v_add_f32_e32 v163, v163, v23
	s_waitcnt lgkmcnt(13)
	v_add_f32_e32 v164, v164, v24
	v_add_f32_e32 v165, v165, v25
	s_waitcnt lgkmcnt(12)
	v_add_f32_e32 v166, v166, v26
	v_add_f32_e32 v167, v167, v27
	s_waitcnt lgkmcnt(11)
	v_add_f32_e32 v168, v168, v28
	v_add_f32_e32 v169, v169, v29
	s_waitcnt lgkmcnt(10)
	v_add_f32_e32 v170, v170, v30
	v_add_f32_e32 v171, v171, v31
	s_waitcnt lgkmcnt(9)
	v_add_f32_e32 v172, v172, v32
	v_add_f32_e32 v173, v173, v33
	s_waitcnt lgkmcnt(8)
	v_add_f32_e32 v174, v174, v34
	v_add_f32_e32 v175, v175, v35
	s_waitcnt lgkmcnt(7)
	v_add_f32_e32 v144, v144, v36
	v_add_f32_e32 v145, v145, v37
	s_waitcnt lgkmcnt(6)
	v_add_f32_e32 v146, v146, v38
	v_add_f32_e32 v147, v147, v39
	s_waitcnt lgkmcnt(5)
	v_add_f32_e32 v148, v148, v40
	v_add_f32_e32 v149, v149, v41
	s_waitcnt lgkmcnt(4)
	v_add_f32_e32 v150, v150, v42
	v_add_f32_e32 v151, v151, v43
	s_waitcnt lgkmcnt(3)
	v_add_f32_e32 v152, v152, v44
	v_add_f32_e32 v153, v153, v45
	s_waitcnt lgkmcnt(2)
	v_add_f32_e32 v154, v154, v46
	v_add_f32_e32 v155, v155, v47
	s_waitcnt lgkmcnt(1)
	v_add_f32_e32 v156, v156, v48
	v_add_f32_e32 v157, v157, v49
	s_waitcnt lgkmcnt(0)
	v_add_f32_e32 v158, v158, v50
	v_add_f32_e32 v159, v159, v51
